# lever 2 (de-serialisation): layer-0 gemmU gate-fold loads issued together (16 loads, one wait) instead of four serial groups
# baseline (speedup 1.0000x reference)
.LBB0_683:
	ds_read_b128 v[160:163], v0 offset:32768
	ds_read_b128 v[164:167], v0 offset:34816
	ds_read_b128 v[168:171], v0 offset:36864
	ds_read_b128 v[194:197], v0 offset:38912
	ds_read_b128 v[198:201], v190 offset:49152
	ds_read_b128 v[202:205], v190 offset:51200
	ds_read_b128 v[206:209], v190 offset:53248
	ds_read_b128 v[210:213], v190 offset:55296
	s_bitcmp0_b32 s92, 1
	s_waitcnt lgkmcnt(0)
	v_mfma_f32_16x16x32_f16 v[68:71], v[198:201], v[160:163], v[68:71]
	v_mfma_f32_16x16x32_f16 v[72:75], v[202:205], v[160:163], v[72:75]
	v_mfma_f32_16x16x32_f16 v[76:79], v[206:209], v[160:163], v[76:79]
	v_mfma_f32_16x16x32_f16 v[80:83], v[210:213], v[160:163], v[80:83]
	v_mfma_f32_16x16x32_f16 v[84:87], v[198:201], v[164:167], v[84:87]
	v_mfma_f32_16x16x32_f16 v[88:91], v[202:205], v[164:167], v[88:91]
	v_mfma_f32_16x16x32_f16 v[92:95], v[206:209], v[164:167], v[92:95]
	v_mfma_f32_16x16x32_f16 v[96:99], v[210:213], v[164:167], v[96:99]
	v_mfma_f32_16x16x32_f16 v[160:163], v[198:201], v[168:171], v[100:103]
	v_mfma_f32_16x16x32_f16 v[164:167], v[202:205], v[168:171], v[104:107]
	v_mfma_f32_16x16x32_f16 v[214:217], v[206:209], v[168:171], v[108:111]
	v_mfma_f32_16x16x32_f16 v[168:171], v[210:213], v[168:171], v[112:115]
	v_mfma_f32_16x16x32_f16 v[198:201], v[198:201], v[194:197], v[116:119]
	v_mfma_f32_16x16x32_f16 v[202:205], v[202:205], v[194:197], v[120:123]
	v_mfma_f32_16x16x32_f16 v[206:209], v[206:209], v[194:197], v[124:127]
	v_mfma_f32_16x16x32_f16 v[194:197], v[210:213], v[194:197], v[128:131]
	ds_read_b128 v[100:103], v191 offset:32768
	ds_read_b128 v[210:213], v191 offset:34816
	ds_read_b128 v[218:221], v191 offset:36864
	ds_read_b128 v[222:225], v191 offset:38912
	ds_read_b128 v[226:229], v192 offset:49152
	ds_read_b128 v[230:233], v192 offset:51200
	ds_read_b128 v[234:237], v192 offset:53248
	ds_read_b128 v[190:193], v192 offset:55296
	s_waitcnt lgkmcnt(0)
	v_mfma_f32_16x16x32_f16 v[128:131], v[226:229], v[100:103], v[68:71]
	v_mfma_f32_16x16x32_f16 v[124:127], v[230:233], v[100:103], v[72:75]
	v_mfma_f32_16x16x32_f16 v[120:123], v[234:237], v[100:103], v[76:79]
	v_mfma_f32_16x16x32_f16 v[116:119], v[190:193], v[100:103], v[80:83]
	v_mfma_f32_16x16x32_f16 v[112:115], v[226:229], v[210:213], v[84:87]
	v_mfma_f32_16x16x32_f16 v[108:111], v[230:233], v[210:213], v[88:91]
	v_mfma_f32_16x16x32_f16 v[104:107], v[234:237], v[210:213], v[92:95]
	v_mfma_f32_16x16x32_f16 v[100:103], v[190:193], v[210:213], v[96:99]
	v_mfma_f32_16x16x32_f16 v[96:99], v[226:229], v[218:221], v[160:163]
	v_mfma_f32_16x16x32_f16 v[92:95], v[230:233], v[218:221], v[164:167]
	v_mfma_f32_16x16x32_f16 v[88:91], v[234:237], v[218:221], v[214:217]
	v_mfma_f32_16x16x32_f16 v[84:87], v[190:193], v[218:221], v[168:171]
	v_mfma_f32_16x16x32_f16 v[80:83], v[226:229], v[222:225], v[198:201]
	v_mfma_f32_16x16x32_f16 v[76:79], v[230:233], v[222:225], v[202:205]
	v_mfma_f32_16x16x32_f16 v[72:75], v[234:237], v[222:225], v[206:209]
	v_mfma_f32_16x16x32_f16 v[68:71], v[190:193], v[222:225], v[194:197]
	s_cbranch_scc1 .LBB0_680
	s_and_b32 s0, s91, 0xc00
	s_lshl_b32 s0, s0, 1
	v_lshl_add_u64 v[2:3], v[136:137], 0, s[0:1]
	v_lshl_add_u64 v[166:167], v[138:139], 0, s[0:1]
	v_lshl_add_u64 v[190:191], v[140:141], 0, s[0:1]
	global_load_dwordx2 v[162:163], v[2:3], off
	global_load_dwordx2 v[164:165], v[2:3], off offset:32
	global_load_dwordx2 v[160:161], v[2:3], off offset:64
	s_nop 0
	global_load_dwordx2 v[2:3], v[2:3], off offset:96
	s_nop 0
	global_load_dwordx2 v[168:169], v[166:167], off
	global_load_dwordx2 v[170:171], v[166:167], off offset:32
	global_load_dwordx2 v[172:173], v[166:167], off offset:64
	s_nop 0
	global_load_dwordx2 v[166:167], v[166:167], off offset:96
	s_nop 0
	global_load_dwordx2 v[192:193], v[190:191], off
	global_load_dwordx2 v[194:195], v[190:191], off offset:32
	global_load_dwordx2 v[196:197], v[190:191], off offset:64
	s_nop 0
	global_load_dwordx2 v[190:191], v[190:191], off offset:96
	v_lshl_add_u64 v[198:199], v[142:143], 0, s[0:1]
	global_load_dwordx2 v[200:201], v[198:199], off
	global_load_dwordx2 v[202:203], v[198:199], off offset:32
	global_load_dwordx2 v[204:205], v[198:199], off offset:64
	s_nop 0
	global_load_dwordx2 v[198:199], v[198:199], off offset:96
	s_waitcnt vmcnt(0)
	v_cvt_f32_f16_e32 v206, v162
	v_cvt_f32_f16_sdwa v207, v162 dst_sel:DWORD dst_unused:UNUSED_PAD src0_sel:WORD_1
	v_cvt_f32_f16_e32 v162, v163
	v_cvt_f32_f16_e32 v212, v2
	v_cvt_f32_f16_e32 v226, v196
	v_cvt_f32_f16_sdwa v227, v196 dst_sel:DWORD dst_unused:UNUSED_PAD src0_sel:WORD_1
	v_cvt_f32_f16_sdwa v213, v2 dst_sel:DWORD dst_unused:UNUSED_PAD src0_sel:WORD_1
	v_cvt_f32_f16_e32 v2, v3
	v_cvt_f32_f16_sdwa v3, v3 dst_sel:DWORD dst_unused:UNUSED_PAD src0_sel:WORD_1
	v_cvt_f32_f16_e32 v230, v191
	v_cvt_f32_f16_sdwa v231, v191 dst_sel:DWORD dst_unused:UNUSED_PAD src0_sel:WORD_1
	v_pk_fma_f32 v[24:25], v[88:89], v[226:227], v[24:25]
	v_cvt_f32_f16_e32 v88, v203
	v_cvt_f32_f16_sdwa v89, v203 dst_sel:DWORD dst_unused:UNUSED_PAD src0_sel:WORD_1
	v_cvt_f32_f16_e32 v228, v190
	v_pk_fma_f32 v[54:55], v[118:119], v[2:3], v[54:55]
	v_cvt_f32_f16_sdwa v229, v190 dst_sel:DWORD dst_unused:UNUSED_PAD src0_sel:WORD_1
	v_pk_fma_f32 v[22:23], v[86:87], v[230:231], v[22:23]
	v_cvt_f32_f16_e32 v2, v200
	v_cvt_f32_f16_sdwa v3, v200 dst_sel:DWORD dst_unused:UNUSED_PAD src0_sel:WORD_1
	v_cvt_f32_f16_e32 v86, v202
	v_cvt_f32_f16_sdwa v87, v202 dst_sel:DWORD dst_unused:UNUSED_PAD src0_sel:WORD_1
	v_pk_fma_f32 v[14:15], v[78:79], v[88:89], v[14:15]
	v_cvt_f32_f16_e32 v78, v198
	v_cvt_f32_f16_sdwa v79, v198 dst_sel:DWORD dst_unused:UNUSED_PAD src0_sel:WORD_1
	v_cvt_f32_f16_sdwa v163, v163 dst_sel:DWORD dst_unused:UNUSED_PAD src0_sel:WORD_1
	v_cvt_f32_f16_e32 v208, v164
	v_cvt_f32_f16_sdwa v209, v164 dst_sel:DWORD dst_unused:UNUSED_PAD src0_sel:WORD_1
	v_cvt_f32_f16_e32 v164, v165
	v_cvt_f32_f16_sdwa v165, v165 dst_sel:DWORD dst_unused:UNUSED_PAD src0_sel:WORD_1
	v_cvt_f32_f16_e32 v210, v160
	v_cvt_f32_f16_sdwa v211, v160 dst_sel:DWORD dst_unused:UNUSED_PAD src0_sel:WORD_1
	v_cvt_f32_f16_e32 v160, v161
	v_cvt_f32_f16_sdwa v161, v161 dst_sel:DWORD dst_unused:UNUSED_PAD src0_sel:WORD_1
	v_cvt_f32_f16_e32 v214, v168
	v_cvt_f32_f16_sdwa v215, v168 dst_sel:DWORD dst_unused:UNUSED_PAD src0_sel:WORD_1
	v_cvt_f32_f16_e32 v168, v169
	v_cvt_f32_f16_sdwa v169, v169 dst_sel:DWORD dst_unused:UNUSED_PAD src0_sel:WORD_1
	v_cvt_f32_f16_e32 v216, v170
	v_cvt_f32_f16_sdwa v217, v170 dst_sel:DWORD dst_unused:UNUSED_PAD src0_sel:WORD_1
	v_cvt_f32_f16_e32 v170, v171
	v_cvt_f32_f16_sdwa v171, v171 dst_sel:DWORD dst_unused:UNUSED_PAD src0_sel:WORD_1
	v_cvt_f32_f16_e32 v218, v172
	v_cvt_f32_f16_sdwa v219, v172 dst_sel:DWORD dst_unused:UNUSED_PAD src0_sel:WORD_1
	v_cvt_f32_f16_e32 v172, v173
	v_cvt_f32_f16_sdwa v173, v173 dst_sel:DWORD dst_unused:UNUSED_PAD src0_sel:WORD_1
	v_cvt_f32_f16_e32 v220, v166
	v_cvt_f32_f16_sdwa v221, v166 dst_sel:DWORD dst_unused:UNUSED_PAD src0_sel:WORD_1
	v_cvt_f32_f16_e32 v166, v167
	v_cvt_f32_f16_sdwa v167, v167 dst_sel:DWORD dst_unused:UNUSED_PAD src0_sel:WORD_1
	v_cvt_f32_f16_e32 v222, v192
	v_cvt_f32_f16_sdwa v223, v192 dst_sel:DWORD dst_unused:UNUSED_PAD src0_sel:WORD_1
	v_cvt_f32_f16_e32 v192, v193
	v_cvt_f32_f16_sdwa v193, v193 dst_sel:DWORD dst_unused:UNUSED_PAD src0_sel:WORD_1
	v_cvt_f32_f16_e32 v224, v194
	v_cvt_f32_f16_sdwa v225, v194 dst_sel:DWORD dst_unused:UNUSED_PAD src0_sel:WORD_1
	v_cvt_f32_f16_e32 v194, v195
	v_cvt_f32_f16_sdwa v195, v195 dst_sel:DWORD dst_unused:UNUSED_PAD src0_sel:WORD_1
	v_cvt_f32_f16_e32 v196, v197
	v_cvt_f32_f16_sdwa v197, v197 dst_sel:DWORD dst_unused:UNUSED_PAD src0_sel:WORD_1
	v_pk_fma_f32 v[20:21], v[84:85], v[228:229], v[20:21]
	v_cvt_f32_f16_e32 v84, v201
	v_cvt_f32_f16_sdwa v85, v201 dst_sel:DWORD dst_unused:UNUSED_PAD src0_sel:WORD_1
	v_pk_fma_f32 v[16:17], v[80:81], v[2:3], v[16:17]
	v_pk_fma_f32 v[12:13], v[76:77], v[86:87], v[12:13]
	v_cvt_f32_f16_e32 v2, v204
	v_cvt_f32_f16_sdwa v3, v204 dst_sel:DWORD dst_unused:UNUSED_PAD src0_sel:WORD_1
	v_cvt_f32_f16_e32 v76, v205
	v_cvt_f32_f16_sdwa v77, v205 dst_sel:DWORD dst_unused:UNUSED_PAD src0_sel:WORD_1
	v_cvt_f32_f16_e32 v80, v199
	v_cvt_f32_f16_sdwa v81, v199 dst_sel:DWORD dst_unused:UNUSED_PAD src0_sel:WORD_1
	v_pk_fma_f32 v[4:5], v[68:69], v[78:79], v[4:5]
	v_mov_b32_e32 v68, 0
	v_pk_fma_f32 v[66:67], v[130:131], v[162:163], v[66:67]
	v_pk_fma_f32 v[64:65], v[128:129], v[206:207], v[64:65]
	v_pk_fma_f32 v[62:63], v[126:127], v[164:165], v[62:63]
	v_pk_fma_f32 v[60:61], v[124:125], v[208:209], v[60:61]
	v_pk_fma_f32 v[58:59], v[122:123], v[160:161], v[58:59]
	v_pk_fma_f32 v[56:57], v[120:121], v[210:211], v[56:57]
	v_pk_fma_f32 v[52:53], v[116:117], v[212:213], v[52:53]
	v_pk_fma_f32 v[50:51], v[114:115], v[168:169], v[50:51]
	v_pk_fma_f32 v[48:49], v[112:113], v[214:215], v[48:49]
	v_pk_fma_f32 v[46:47], v[110:111], v[170:171], v[46:47]
	v_pk_fma_f32 v[44:45], v[108:109], v[216:217], v[44:45]
	v_pk_fma_f32 v[42:43], v[106:107], v[172:173], v[42:43]
	v_pk_fma_f32 v[40:41], v[104:105], v[218:219], v[40:41]
	v_pk_fma_f32 v[38:39], v[102:103], v[166:167], v[38:39]
	v_pk_fma_f32 v[36:37], v[100:101], v[220:221], v[36:37]
	v_pk_fma_f32 v[34:35], v[98:99], v[192:193], v[34:35]
	v_pk_fma_f32 v[32:33], v[96:97], v[222:223], v[32:33]
	v_pk_fma_f32 v[30:31], v[94:95], v[194:195], v[30:31]
	v_pk_fma_f32 v[28:29], v[92:93], v[224:225], v[28:29]
	v_pk_fma_f32 v[26:27], v[90:91], v[196:197], v[26:27]
	v_pk_fma_f32 v[18:19], v[82:83], v[84:85], v[18:19]
	v_pk_fma_f32 v[10:11], v[74:75], v[76:77], v[10:11]
	v_pk_fma_f32 v[8:9], v[72:73], v[2:3], v[8:9]
	v_pk_fma_f32 v[6:7], v[70:71], v[80:81], v[6:7]
	v_mov_b32_e32 v69, v68
	v_mov_b32_e32 v70, v68
	v_mov_b32_e32 v71, v68
	v_mov_b32_e32 v72, v68
	v_mov_b32_e32 v73, v68
	v_mov_b32_e32 v74, v68
	v_mov_b32_e32 v75, v68
	v_mov_b32_e32 v76, v68
	v_mov_b32_e32 v77, v68
	v_mov_b32_e32 v78, v68
	v_mov_b32_e32 v79, v68
	v_mov_b32_e32 v80, v68
	v_mov_b32_e32 v81, v68
	v_mov_b32_e32 v82, v68
	v_mov_b32_e32 v83, v68
	v_mov_b32_e32 v84, v68
	v_mov_b32_e32 v85, v68
	v_mov_b32_e32 v86, v68
	v_mov_b32_e32 v87, v68
	v_mov_b32_e32 v88, v68
	v_mov_b32_e32 v89, v68
	v_mov_b32_e32 v90, v68
	v_mov_b32_e32 v91, v68
	v_mov_b32_e32 v92, v68
	v_mov_b32_e32 v93, v68
	v_mov_b32_e32 v94, v68
	v_mov_b32_e32 v95, v68
	v_mov_b32_e32 v96, v68
	v_mov_b32_e32 v97, v68
	v_mov_b32_e32 v98, v68
	v_mov_b32_e32 v99, v68
	v_mov_b32_e32 v100, v68
	v_mov_b32_e32 v101, v68
	v_mov_b32_e32 v102, v68
	v_mov_b32_e32 v103, v68
	v_mov_b32_e32 v104, v68
	v_mov_b32_e32 v105, v68
	v_mov_b32_e32 v106, v68
	v_mov_b32_e32 v107, v68
	v_mov_b32_e32 v108, v68
	v_mov_b32_e32 v109, v68
	v_mov_b32_e32 v110, v68
	v_mov_b32_e32 v111, v68
	v_mov_b32_e32 v112, v68
	v_mov_b32_e32 v113, v68
	v_mov_b32_e32 v114, v68
	v_mov_b32_e32 v115, v68
	v_mov_b32_e32 v116, v68
	v_mov_b32_e32 v117, v68
	v_mov_b32_e32 v118, v68
	v_mov_b32_e32 v119, v68
	v_mov_b32_e32 v120, v68
	v_mov_b32_e32 v121, v68
	v_mov_b32_e32 v122, v68
	v_mov_b32_e32 v123, v68
	v_mov_b32_e32 v124, v68
	v_mov_b32_e32 v125, v68
	v_mov_b32_e32 v126, v68
	v_mov_b32_e32 v127, v68
	v_mov_b32_e32 v128, v68
	v_mov_b32_e32 v129, v68
	v_mov_b32_e32 v130, v68
	v_mov_b32_e32 v131, v68
	s_branch .LBB0_680
